# out/down-proj residual epilogue rewritten by hand (second-half base loads issued before first-half stores, scalar-base addressing), padded to the old size so all other code keeps its address
# baseline (speedup 1.0000x reference)
;     __device__ __forceinline__ void operator()(const f32x4 (&acc)[2][2][4][2], const Unit& u, int wr, int wc, int fr, int fq) const {
;         const int col0 = u.pn * BM + wc * 32 + 4 * fq;
;         const int rbase = row_off + u.pm * BM;
;         const float* gp = gate + (size_t)(rbase >> 13) * 6144 + col0;
;         f32x4 gv[2][2];
; #pragma unroll
;         for (int bj = 0; bj < 2; ++bj)
; #pragma unroll
;             for (int n = 0; n < 2; ++n) gv[bj][n] = *(const f32x4*)(gp + bj * HALF + n * 16);
; #pragma unroll
;         for (int ai = 0; ai < 2; ++ai) {
;             f32x4 bs[4][2][2];
; #pragma unroll
;             for (int m = 0; m < 4; ++m) { const size_t off = (size_t)(rbase + ai * HALF + wr * 64 + m * 16 + fr) * 1024 + col0;
; #pragma unroll
;                 for (int bj = 0; bj < 2; ++bj)
; #pragma unroll
;                     for (int n = 0; n < 2; ++n) bs[m][bj][n] = *(const f32x4*)(base + off + bj * HALF + n * 16); }
;             __builtin_amdgcn_sched_barrier(0);
; #pragma unroll
;             for (int m = 0; m < 4; ++m) { const size_t off = (size_t)(rbase + ai * HALF + wr * 64 + m * 16 + fr) * 1024 + col0;
; #pragma unroll
;                 for (int bj = 0; bj < 2; ++bj)
; #pragma unroll
;                     for (int n = 0; n < 2; ++n) *(f32x4*)(out + off + bj * HALF + n * 16) = bs[m][bj][n] + gv[bj][n] * acc[ai][bj][m][n]; }
;             __builtin_amdgcn_sched_barrier(0);
;         }
;     }
.LBB0_123:
	v_lshl_or_b32 v152, s92, 8, v160
	v_lshlrev_b32_e32 v152, 2, v152
	v_lshl_add_u32 v156, s84, 8, v158
	v_lshl_add_u32 v156, v156, 12, v152
	s_lshr_b32 s24, s84, 5
	s_mul_i32 s24, s24, 0x6000
	s_add_u32 s24, s74, s24
	s_addc_u32 s25, s75, 0
	global_load_dwordx4 v[142:145], v152, s[24:25]
	global_load_dwordx4 v[138:141], v152, s[24:25] offset:64
	global_load_dwordx4 v[134:137], v152, s[24:25] offset:512
	global_load_dwordx4 v[130:133], v152, s[24:25] offset:576
	s_add_u32 s98, s18, 0x0
	s_addc_u32 s99, s19, 0
	global_load_dwordx4 v[162:165], v156, s[98:99]
	global_load_dwordx4 v[166:169], v156, s[98:99] offset:64
	global_load_dwordx4 v[178:181], v156, s[98:99] offset:512
	global_load_dwordx4 v[182:185], v156, s[98:99] offset:576
	s_add_u32 s98, s18, 0x10000
	s_addc_u32 s99, s19, 0
	global_load_dwordx4 v[186:189], v156, s[98:99]
	global_load_dwordx4 v[190:193], v156, s[98:99] offset:64
	global_load_dwordx4 v[194:197], v156, s[98:99] offset:512
	global_load_dwordx4 v[198:201], v156, s[98:99] offset:576
	s_add_u32 s98, s18, 0x20000
	s_addc_u32 s99, s19, 0
	global_load_dwordx4 v[202:205], v156, s[98:99]
	global_load_dwordx4 v[206:209], v156, s[98:99] offset:64
	global_load_dwordx4 v[224:227], v156, s[98:99] offset:512
	global_load_dwordx4 v[228:231], v156, s[98:99] offset:576
	s_add_u32 s98, s18, 0x30000
	s_addc_u32 s99, s19, 0
	global_load_dwordx4 v[232:235], v156, s[98:99]
	global_load_dwordx4 v[236:239], v156, s[98:99] offset:64
	global_load_dwordx4 v[240:243], v156, s[98:99] offset:512
	global_load_dwordx4 v[244:247], v156, s[98:99] offset:576
	s_waitcnt vmcnt(0)
	v_pk_fma_f32 v[126:127], v[126:127], v[142:143], v[162:163]
	v_pk_fma_f32 v[128:129], v[128:129], v[144:145], v[164:165]
	v_pk_fma_f32 v[122:123], v[122:123], v[138:139], v[166:167]
	v_pk_fma_f32 v[124:125], v[124:125], v[140:141], v[168:169]
	v_pk_fma_f32 v[114:115], v[114:115], v[134:135], v[178:179]
	v_pk_fma_f32 v[116:117], v[116:117], v[136:137], v[180:181]
	v_pk_fma_f32 v[106:107], v[106:107], v[130:131], v[182:183]
	v_pk_fma_f32 v[108:109], v[108:109], v[132:133], v[184:185]
	v_pk_fma_f32 v[118:119], v[118:119], v[142:143], v[186:187]
	v_pk_fma_f32 v[120:121], v[120:121], v[144:145], v[188:189]
	v_pk_fma_f32 v[110:111], v[110:111], v[138:139], v[190:191]
	v_pk_fma_f32 v[112:113], v[112:113], v[140:141], v[192:193]
	v_pk_fma_f32 v[98:99], v[98:99], v[134:135], v[194:195]
	v_pk_fma_f32 v[100:101], v[100:101], v[136:137], v[196:197]
	v_pk_fma_f32 v[90:91], v[90:91], v[130:131], v[198:199]
	v_pk_fma_f32 v[92:93], v[92:93], v[132:133], v[200:201]
	v_pk_fma_f32 v[102:103], v[102:103], v[142:143], v[202:203]
	v_pk_fma_f32 v[104:105], v[104:105], v[144:145], v[204:205]
	v_pk_fma_f32 v[94:95], v[94:95], v[138:139], v[206:207]
	v_pk_fma_f32 v[96:97], v[96:97], v[140:141], v[208:209]
	v_pk_fma_f32 v[82:83], v[82:83], v[134:135], v[224:225]
	v_pk_fma_f32 v[84:85], v[84:85], v[136:137], v[226:227]
	v_pk_fma_f32 v[74:75], v[74:75], v[130:131], v[228:229]
	v_pk_fma_f32 v[76:77], v[76:77], v[132:133], v[230:231]
	v_pk_fma_f32 v[86:87], v[86:87], v[142:143], v[232:233]
	v_pk_fma_f32 v[88:89], v[88:89], v[144:145], v[234:235]
	v_pk_fma_f32 v[78:79], v[78:79], v[138:139], v[236:237]
	v_pk_fma_f32 v[80:81], v[80:81], v[140:141], v[238:239]
	v_pk_fma_f32 v[70:71], v[70:71], v[134:135], v[240:241]
	v_pk_fma_f32 v[72:73], v[72:73], v[136:137], v[242:243]
	v_pk_fma_f32 v[66:67], v[66:67], v[130:131], v[244:245]
	v_pk_fma_f32 v[68:69], v[68:69], v[132:133], v[246:247]
	s_add_u32 s98, s18, 0x80000
	s_addc_u32 s99, s19, 0
	global_load_dwordx4 v[162:165], v156, s[98:99]
	global_load_dwordx4 v[166:169], v156, s[98:99] offset:64
	global_load_dwordx4 v[178:181], v156, s[98:99] offset:512
	global_load_dwordx4 v[182:185], v156, s[98:99] offset:576
	s_add_u32 s98, s18, 0x90000
	s_addc_u32 s99, s19, 0
	global_load_dwordx4 v[186:189], v156, s[98:99]
	global_load_dwordx4 v[190:193], v156, s[98:99] offset:64
	global_load_dwordx4 v[194:197], v156, s[98:99] offset:512
	global_load_dwordx4 v[198:201], v156, s[98:99] offset:576
	s_add_u32 s98, s18, 0xa0000
	s_addc_u32 s99, s19, 0
	global_load_dwordx4 v[202:205], v156, s[98:99]
	global_load_dwordx4 v[206:209], v156, s[98:99] offset:64
	global_load_dwordx4 v[224:227], v156, s[98:99] offset:512
	global_load_dwordx4 v[228:231], v156, s[98:99] offset:576
	s_add_u32 s98, s18, 0xb0000
	s_addc_u32 s99, s19, 0
	global_load_dwordx4 v[232:235], v156, s[98:99]
	global_load_dwordx4 v[236:239], v156, s[98:99] offset:64
	global_load_dwordx4 v[240:243], v156, s[98:99] offset:512
	global_load_dwordx4 v[244:247], v156, s[98:99] offset:576
	s_add_u32 vcc_lo, s18, 0x0
	s_addc_u32 vcc_hi, s19, 0
	global_store_dwordx4 v156, v[126:129], vcc
	global_store_dwordx4 v156, v[122:125], vcc offset:64
	global_store_dwordx4 v156, v[114:117], vcc offset:512
	global_store_dwordx4 v156, v[106:109], vcc offset:576
	s_add_u32 vcc_lo, s18, 0x10000
	s_addc_u32 vcc_hi, s19, 0
	global_store_dwordx4 v156, v[118:121], vcc
	global_store_dwordx4 v156, v[110:113], vcc offset:64
	global_store_dwordx4 v156, v[98:101], vcc offset:512
	global_store_dwordx4 v156, v[90:93], vcc offset:576
	s_add_u32 vcc_lo, s18, 0x20000
	s_addc_u32 vcc_hi, s19, 0
	global_store_dwordx4 v156, v[102:105], vcc
	global_store_dwordx4 v156, v[94:97], vcc offset:64
	global_store_dwordx4 v156, v[82:85], vcc offset:512
	global_store_dwordx4 v156, v[74:77], vcc offset:576
	s_add_u32 vcc_lo, s18, 0x30000
	s_addc_u32 vcc_hi, s19, 0
	global_store_dwordx4 v156, v[86:89], vcc
	global_store_dwordx4 v156, v[78:81], vcc offset:64
	global_store_dwordx4 v156, v[70:73], vcc offset:512
	global_store_dwordx4 v156, v[66:69], vcc offset:576
	s_waitcnt vmcnt(16)
; #define PG8_BAR __builtin_amdgcn_s_barrier()
; template <class Epi, class Sched, bool ALIGN_EPI = false, bool SP2 = false>
; __device__ __forceinline__ void gemm_phase(PG8_LAS unsigned char* lds, const Gemm g, const Sched& S, const Epi& E) {
;     ...
;         if constexpr (ALIGN_EPI) { if (wr == 0) PG8_BAR; }
;         if constexpr (!Epi::AFTER_DRAIN) { E(acc, cur, wr, wc, fr, fq); S.done(cur); }
;         if (!has_next) break;
; #pragma unroll
;         for (int a = 0; a < 2; ++a)
; #pragma unroll
;             for (int b = 0; b < 2; ++b)
; #pragma unroll
;                 for (int m = 0; m < 4; ++m)
; #pragma unroll
;                     for (int n = 0; n < 2; ++n) acc[a][b][m][n] = (f32x4){0.f, 0.f, 0.f, 0.f};
;         cur = nxt; cA = nA; cB = nB; ++ui;
;         if constexpr (ALIGN_EPI) { if (wr == 1) PG8_BAR; }
;     }
;     __device__ __forceinline__ void operator()(const f32x4 (&acc)[2][2][4][2], const Unit& u, int wr, int wc, int fr, int fq) const {
;     ...
;             for (int m = 0; m < 4; ++m) { const size_t off = (size_t)(rbase + ai * HALF + wr * 64 + m * 16 + fr) * 1024 + col0;
; #pragma unroll
;                 for (int bj = 0; bj < 2; ++bj)
; #pragma unroll
;                     for (int n = 0; n < 2; ++n) *(f32x4*)(out + off + bj * HALF + n * 16) = bs[m][bj][n] + gv[bj][n] * acc[ai][bj][m][n]; }
;             __builtin_amdgcn_sched_barrier(0);
	v_pk_fma_f32 v[62:63], v[62:63], v[142:143], v[162:163]
	v_pk_fma_f32 v[64:65], v[64:65], v[144:145], v[164:165]
	v_pk_fma_f32 v[58:59], v[58:59], v[138:139], v[166:167]
	v_pk_fma_f32 v[60:61], v[60:61], v[140:141], v[168:169]
	v_pk_fma_f32 v[50:51], v[50:51], v[134:135], v[178:179]
	v_pk_fma_f32 v[52:53], v[52:53], v[136:137], v[180:181]
	v_pk_fma_f32 v[42:43], v[42:43], v[130:131], v[182:183]
	v_pk_fma_f32 v[44:45], v[44:45], v[132:133], v[184:185]
	v_pk_fma_f32 v[54:55], v[54:55], v[142:143], v[186:187]
	v_pk_fma_f32 v[56:57], v[56:57], v[144:145], v[188:189]
	v_pk_fma_f32 v[46:47], v[46:47], v[138:139], v[190:191]
	v_pk_fma_f32 v[48:49], v[48:49], v[140:141], v[192:193]
	v_pk_fma_f32 v[34:35], v[34:35], v[134:135], v[194:195]
	v_pk_fma_f32 v[36:37], v[36:37], v[136:137], v[196:197]
	v_pk_fma_f32 v[26:27], v[26:27], v[130:131], v[198:199]
	v_pk_fma_f32 v[28:29], v[28:29], v[132:133], v[200:201]
	v_pk_fma_f32 v[38:39], v[38:39], v[142:143], v[202:203]
	v_pk_fma_f32 v[40:41], v[40:41], v[144:145], v[204:205]
	v_pk_fma_f32 v[30:31], v[30:31], v[138:139], v[206:207]
	v_pk_fma_f32 v[32:33], v[32:33], v[140:141], v[208:209]
	v_pk_fma_f32 v[18:19], v[18:19], v[134:135], v[224:225]
	v_pk_fma_f32 v[20:21], v[20:21], v[136:137], v[226:227]
	v_pk_fma_f32 v[10:11], v[10:11], v[130:131], v[228:229]
	v_pk_fma_f32 v[12:13], v[12:13], v[132:133], v[230:231]
	v_pk_fma_f32 v[22:23], v[22:23], v[142:143], v[232:233]
	v_pk_fma_f32 v[24:25], v[24:25], v[144:145], v[234:235]
	v_pk_fma_f32 v[14:15], v[14:15], v[138:139], v[236:237]
	v_pk_fma_f32 v[16:17], v[16:17], v[140:141], v[238:239]
	v_pk_fma_f32 v[6:7], v[6:7], v[134:135], v[240:241]
	v_pk_fma_f32 v[8:9], v[8:9], v[136:137], v[242:243]
	v_pk_fma_f32 v[2:3], v[2:3], v[130:131], v[244:245]
	v_pk_fma_f32 v[4:5], v[4:5], v[132:133], v[246:247]
	s_add_u32 vcc_lo, s18, 0x80000
	s_addc_u32 vcc_hi, s19, 0
	global_store_dwordx4 v156, v[62:65], vcc
	global_store_dwordx4 v156, v[58:61], vcc offset:64
	global_store_dwordx4 v156, v[50:53], vcc offset:512
	global_store_dwordx4 v156, v[42:45], vcc offset:576
	s_add_u32 vcc_lo, s18, 0x90000
	s_addc_u32 vcc_hi, s19, 0
	global_store_dwordx4 v156, v[54:57], vcc
	global_store_dwordx4 v156, v[46:49], vcc offset:64
	global_store_dwordx4 v156, v[34:37], vcc offset:512
	global_store_dwordx4 v156, v[26:29], vcc offset:576
	s_add_u32 vcc_lo, s18, 0xa0000
	s_addc_u32 vcc_hi, s19, 0
	global_store_dwordx4 v156, v[38:41], vcc
	global_store_dwordx4 v156, v[30:33], vcc offset:64
	global_store_dwordx4 v156, v[18:21], vcc offset:512
	global_store_dwordx4 v156, v[10:13], vcc offset:576
	s_add_u32 vcc_lo, s18, 0xb0000
	s_addc_u32 vcc_hi, s19, 0
	global_store_dwordx4 v156, v[22:25], vcc
	global_store_dwordx4 v156, v[14:17], vcc offset:64
	global_store_dwordx4 v156, v[6:9], vcc offset:512
	global_store_dwordx4 v156, v[2:5], vcc offset:576
	s_branch .Lres_pad1
	s_nop 0
	s_nop 0
	s_nop 0
	s_nop 0
	s_nop 0
	s_nop 0
	s_nop 0
	s_nop 0
	s_nop 0
	s_nop 0
	s_nop 0
	s_nop 0
	s_nop 0
	s_nop 0
	s_nop 0
	s_nop 0
	s_nop 0
	s_nop 0
	s_nop 0
	s_nop 0
	s_nop 0
	s_nop 0
	s_nop 0
	s_nop 0
	s_nop 0
	s_nop 0
	s_nop 0
	s_nop 0
	s_nop 0
	s_nop 0
	s_nop 0
	s_nop 0
	s_nop 0
	s_nop 0
	s_nop 0
	s_nop 0
	s_nop 0
	s_nop 0
	s_nop 0
	s_nop 0
	s_nop 0
	s_nop 0
	s_nop 0
	s_nop 0
	s_nop 0
	s_nop 0
	s_nop 0
	s_nop 0
	s_nop 0
	s_nop 0
	s_nop 0
	s_nop 0
	s_nop 0
	s_nop 0
	s_nop 0
	s_nop 0
	s_nop 0
	s_nop 0
.Lres_pad1:
	s_and_b64 vcc, exec, s[6:7]
	s_mov_b64 s[6:7], -1
	s_cbranch_vccnz .LBB0_108
	s_andn2_b64 vcc, exec, s[12:13]
	s_cbranch_vccnz .LBB0_107
	s_barrier
	s_branch .LBB0_107

;     __device__ __forceinline__ void operator()(const f32x4 (&acc)[2][2][4][2], const Unit& u, int wr, int wc, int fr, int fq) const {
;         const int col0 = u.pn * BM + wc * 32 + 4 * fq;
;         const int rbase = row_off + u.pm * BM;
;         const float* gp = gate + (size_t)(rbase >> 13) * 6144 + col0;
;         f32x4 gv[2][2];
; #pragma unroll
;         for (int bj = 0; bj < 2; ++bj)
; #pragma unroll
;             for (int n = 0; n < 2; ++n) gv[bj][n] = *(const f32x4*)(gp + bj * HALF + n * 16);
; #pragma unroll
;         for (int ai = 0; ai < 2; ++ai) {
;             f32x4 bs[4][2][2];
; #pragma unroll
;             for (int m = 0; m < 4; ++m) { const size_t off = (size_t)(rbase + ai * HALF + wr * 64 + m * 16 + fr) * 1024 + col0;
; #pragma unroll
;                 for (int bj = 0; bj < 2; ++bj)
; #pragma unroll
;                     for (int n = 0; n < 2; ++n) bs[m][bj][n] = *(const f32x4*)(base + off + bj * HALF + n * 16); }
;             __builtin_amdgcn_sched_barrier(0);
; #pragma unroll
;             for (int m = 0; m < 4; ++m) { const size_t off = (size_t)(rbase + ai * HALF + wr * 64 + m * 16 + fr) * 1024 + col0;
; #pragma unroll
;                 for (int bj = 0; bj < 2; ++bj)
; #pragma unroll
;                     for (int n = 0; n < 2; ++n) *(f32x4*)(out + off + bj * HALF + n * 16) = bs[m][bj][n] + gv[bj][n] * acc[ai][bj][m][n]; }
;             __builtin_amdgcn_sched_barrier(0);
;         }
;     }
.LBB0_156:
	v_lshl_or_b32 v152, s77, 8, v160
	v_lshlrev_b32_e32 v152, 2, v152
	v_lshl_add_u32 v156, s22, 8, v158
	v_lshl_add_u32 v156, v156, 12, v152
	s_lshr_b32 s24, s22, 5
	s_mul_i32 s24, s24, 0x6000
	s_add_u32 s24, s55, s24
	s_addc_u32 s25, s72, 0
	global_load_dwordx4 v[142:145], v152, s[24:25]
	global_load_dwordx4 v[138:141], v152, s[24:25] offset:64
	global_load_dwordx4 v[134:137], v152, s[24:25] offset:512
	global_load_dwordx4 v[130:133], v152, s[24:25] offset:576
	v_readlane_b32 s24, v255, 5
	v_readlane_b32 s25, v255, 6
	s_add_u32 s98, s24, 0x0
	s_addc_u32 s99, s25, 0
	global_load_dwordx4 v[162:165], v156, s[98:99]
	global_load_dwordx4 v[166:169], v156, s[98:99] offset:64
	global_load_dwordx4 v[178:181], v156, s[98:99] offset:512
	global_load_dwordx4 v[182:185], v156, s[98:99] offset:576
	s_add_u32 s98, s24, 0x10000
	s_addc_u32 s99, s25, 0
	global_load_dwordx4 v[186:189], v156, s[98:99]
	global_load_dwordx4 v[190:193], v156, s[98:99] offset:64
	global_load_dwordx4 v[194:197], v156, s[98:99] offset:512
	global_load_dwordx4 v[198:201], v156, s[98:99] offset:576
	s_add_u32 s98, s24, 0x20000
	s_addc_u32 s99, s25, 0
	global_load_dwordx4 v[202:205], v156, s[98:99]
	global_load_dwordx4 v[206:209], v156, s[98:99] offset:64
	global_load_dwordx4 v[224:227], v156, s[98:99] offset:512
	global_load_dwordx4 v[228:231], v156, s[98:99] offset:576
	s_add_u32 s98, s24, 0x30000
	s_addc_u32 s99, s25, 0
	global_load_dwordx4 v[232:235], v156, s[98:99]
	global_load_dwordx4 v[236:239], v156, s[98:99] offset:64
	global_load_dwordx4 v[240:243], v156, s[98:99] offset:512
	global_load_dwordx4 v[244:247], v156, s[98:99] offset:576
	s_waitcnt vmcnt(0)
	v_pk_fma_f32 v[126:127], v[126:127], v[142:143], v[162:163]
	v_pk_fma_f32 v[128:129], v[128:129], v[144:145], v[164:165]
	v_pk_fma_f32 v[122:123], v[122:123], v[138:139], v[166:167]
	v_pk_fma_f32 v[124:125], v[124:125], v[140:141], v[168:169]
	v_pk_fma_f32 v[114:115], v[114:115], v[134:135], v[178:179]
	v_pk_fma_f32 v[116:117], v[116:117], v[136:137], v[180:181]
	v_pk_fma_f32 v[106:107], v[106:107], v[130:131], v[182:183]
	v_pk_fma_f32 v[108:109], v[108:109], v[132:133], v[184:185]
	v_pk_fma_f32 v[118:119], v[118:119], v[142:143], v[186:187]
	v_pk_fma_f32 v[120:121], v[120:121], v[144:145], v[188:189]
	v_pk_fma_f32 v[110:111], v[110:111], v[138:139], v[190:191]
	v_pk_fma_f32 v[112:113], v[112:113], v[140:141], v[192:193]
	v_pk_fma_f32 v[98:99], v[98:99], v[134:135], v[194:195]
	v_pk_fma_f32 v[100:101], v[100:101], v[136:137], v[196:197]
	v_pk_fma_f32 v[90:91], v[90:91], v[130:131], v[198:199]
	v_pk_fma_f32 v[92:93], v[92:93], v[132:133], v[200:201]
	v_pk_fma_f32 v[102:103], v[102:103], v[142:143], v[202:203]
	v_pk_fma_f32 v[104:105], v[104:105], v[144:145], v[204:205]
	v_pk_fma_f32 v[94:95], v[94:95], v[138:139], v[206:207]
	v_pk_fma_f32 v[96:97], v[96:97], v[140:141], v[208:209]
	v_pk_fma_f32 v[82:83], v[82:83], v[134:135], v[224:225]
	v_pk_fma_f32 v[84:85], v[84:85], v[136:137], v[226:227]
	v_pk_fma_f32 v[74:75], v[74:75], v[130:131], v[228:229]
	v_pk_fma_f32 v[76:77], v[76:77], v[132:133], v[230:231]
	v_pk_fma_f32 v[86:87], v[86:87], v[142:143], v[232:233]
	v_pk_fma_f32 v[88:89], v[88:89], v[144:145], v[234:235]
	v_pk_fma_f32 v[78:79], v[78:79], v[138:139], v[236:237]
	v_pk_fma_f32 v[80:81], v[80:81], v[140:141], v[238:239]
	v_pk_fma_f32 v[70:71], v[70:71], v[134:135], v[240:241]
	v_pk_fma_f32 v[72:73], v[72:73], v[136:137], v[242:243]
	v_pk_fma_f32 v[66:67], v[66:67], v[130:131], v[244:245]
	v_pk_fma_f32 v[68:69], v[68:69], v[132:133], v[246:247]
	s_add_u32 s98, s24, 0x80000
	s_addc_u32 s99, s25, 0
	global_load_dwordx4 v[162:165], v156, s[98:99]
	global_load_dwordx4 v[166:169], v156, s[98:99] offset:64
	global_load_dwordx4 v[178:181], v156, s[98:99] offset:512
	global_load_dwordx4 v[182:185], v156, s[98:99] offset:576
	s_add_u32 s98, s24, 0x90000
	s_addc_u32 s99, s25, 0
	global_load_dwordx4 v[186:189], v156, s[98:99]
	global_load_dwordx4 v[190:193], v156, s[98:99] offset:64
	global_load_dwordx4 v[194:197], v156, s[98:99] offset:512
	global_load_dwordx4 v[198:201], v156, s[98:99] offset:576
	s_add_u32 s98, s24, 0xa0000
	s_addc_u32 s99, s25, 0
	global_load_dwordx4 v[202:205], v156, s[98:99]
	global_load_dwordx4 v[206:209], v156, s[98:99] offset:64
	global_load_dwordx4 v[224:227], v156, s[98:99] offset:512
	global_load_dwordx4 v[228:231], v156, s[98:99] offset:576
	s_add_u32 s98, s24, 0xb0000
	s_addc_u32 s99, s25, 0
	global_load_dwordx4 v[232:235], v156, s[98:99]
	global_load_dwordx4 v[236:239], v156, s[98:99] offset:64
	global_load_dwordx4 v[240:243], v156, s[98:99] offset:512
	global_load_dwordx4 v[244:247], v156, s[98:99] offset:576
	s_add_u32 vcc_lo, s18, 0x0
	s_addc_u32 vcc_hi, s19, 0
	global_store_dwordx4 v156, v[126:129], vcc
	global_store_dwordx4 v156, v[122:125], vcc offset:64
	global_store_dwordx4 v156, v[114:117], vcc offset:512
	global_store_dwordx4 v156, v[106:109], vcc offset:576
	s_add_u32 vcc_lo, s18, 0x10000
	s_addc_u32 vcc_hi, s19, 0
	global_store_dwordx4 v156, v[118:121], vcc
	global_store_dwordx4 v156, v[110:113], vcc offset:64
	global_store_dwordx4 v156, v[98:101], vcc offset:512
	global_store_dwordx4 v156, v[90:93], vcc offset:576
	s_add_u32 vcc_lo, s18, 0x20000
	s_addc_u32 vcc_hi, s19, 0
	global_store_dwordx4 v156, v[102:105], vcc
	global_store_dwordx4 v156, v[94:97], vcc offset:64
	global_store_dwordx4 v156, v[82:85], vcc offset:512
	global_store_dwordx4 v156, v[74:77], vcc offset:576
	s_add_u32 vcc_lo, s18, 0x30000
	s_addc_u32 vcc_hi, s19, 0
	global_store_dwordx4 v156, v[86:89], vcc
	global_store_dwordx4 v156, v[78:81], vcc offset:64
	global_store_dwordx4 v156, v[70:73], vcc offset:512
	global_store_dwordx4 v156, v[66:69], vcc offset:576
	s_waitcnt vmcnt(16)
; #define PG8_BAR __builtin_amdgcn_s_barrier()
; template <class Epi, class Sched, bool ALIGN_EPI = false, bool SP2 = false>
; __device__ __forceinline__ void gemm_phase(PG8_LAS unsigned char* lds, const Gemm g, const Sched& S, const Epi& E) {
;     ...
;         if constexpr (ALIGN_EPI) { if (wr == 0) PG8_BAR; }
;         if constexpr (!Epi::AFTER_DRAIN) { E(acc, cur, wr, wc, fr, fq); S.done(cur); }
;         if (!has_next) break;
; #pragma unroll
;         for (int a = 0; a < 2; ++a)
; #pragma unroll
;             for (int b = 0; b < 2; ++b)
; #pragma unroll
;                 for (int m = 0; m < 4; ++m)
; #pragma unroll
;                     for (int n = 0; n < 2; ++n) acc[a][b][m][n] = (f32x4){0.f, 0.f, 0.f, 0.f};
;         cur = nxt; cA = nA; cB = nB; ++ui;
;         if constexpr (ALIGN_EPI) { if (wr == 1) PG8_BAR; }
;     }
;     __device__ __forceinline__ void operator()(const f32x4 (&acc)[2][2][4][2], const Unit& u, int wr, int wc, int fr, int fq) const {
;     ...
;             for (int m = 0; m < 4; ++m) { const size_t off = (size_t)(rbase + ai * HALF + wr * 64 + m * 16 + fr) * 1024 + col0;
; #pragma unroll
;                 for (int bj = 0; bj < 2; ++bj)
; #pragma unroll
;                     for (int n = 0; n < 2; ++n) *(f32x4*)(out + off + bj * HALF + n * 16) = bs[m][bj][n] + gv[bj][n] * acc[ai][bj][m][n]; }
;             __builtin_amdgcn_sched_barrier(0);
	v_pk_fma_f32 v[62:63], v[62:63], v[142:143], v[162:163]
	v_pk_fma_f32 v[64:65], v[64:65], v[144:145], v[164:165]
	v_pk_fma_f32 v[58:59], v[58:59], v[138:139], v[166:167]
	v_pk_fma_f32 v[60:61], v[60:61], v[140:141], v[168:169]
	v_pk_fma_f32 v[50:51], v[50:51], v[134:135], v[178:179]
	v_pk_fma_f32 v[52:53], v[52:53], v[136:137], v[180:181]
	v_pk_fma_f32 v[42:43], v[42:43], v[130:131], v[182:183]
	v_pk_fma_f32 v[44:45], v[44:45], v[132:133], v[184:185]
	v_pk_fma_f32 v[54:55], v[54:55], v[142:143], v[186:187]
	v_pk_fma_f32 v[56:57], v[56:57], v[144:145], v[188:189]
	v_pk_fma_f32 v[46:47], v[46:47], v[138:139], v[190:191]
	v_pk_fma_f32 v[48:49], v[48:49], v[140:141], v[192:193]
	v_pk_fma_f32 v[34:35], v[34:35], v[134:135], v[194:195]
	v_pk_fma_f32 v[36:37], v[36:37], v[136:137], v[196:197]
	v_pk_fma_f32 v[26:27], v[26:27], v[130:131], v[198:199]
	v_pk_fma_f32 v[28:29], v[28:29], v[132:133], v[200:201]
	v_pk_fma_f32 v[38:39], v[38:39], v[142:143], v[202:203]
	v_pk_fma_f32 v[40:41], v[40:41], v[144:145], v[204:205]
	v_pk_fma_f32 v[30:31], v[30:31], v[138:139], v[206:207]
	v_pk_fma_f32 v[32:33], v[32:33], v[140:141], v[208:209]
	v_pk_fma_f32 v[18:19], v[18:19], v[134:135], v[224:225]
	v_pk_fma_f32 v[20:21], v[20:21], v[136:137], v[226:227]
	v_pk_fma_f32 v[10:11], v[10:11], v[130:131], v[228:229]
	v_pk_fma_f32 v[12:13], v[12:13], v[132:133], v[230:231]
	v_pk_fma_f32 v[22:23], v[22:23], v[142:143], v[232:233]
	v_pk_fma_f32 v[24:25], v[24:25], v[144:145], v[234:235]
	v_pk_fma_f32 v[14:15], v[14:15], v[138:139], v[236:237]
	v_pk_fma_f32 v[16:17], v[16:17], v[140:141], v[238:239]
	v_pk_fma_f32 v[6:7], v[6:7], v[134:135], v[240:241]
	v_pk_fma_f32 v[8:9], v[8:9], v[136:137], v[242:243]
	v_pk_fma_f32 v[2:3], v[2:3], v[130:131], v[244:245]
	v_pk_fma_f32 v[4:5], v[4:5], v[132:133], v[246:247]
	s_add_u32 vcc_lo, s18, 0x80000
	s_addc_u32 vcc_hi, s19, 0
	global_store_dwordx4 v156, v[62:65], vcc
	global_store_dwordx4 v156, v[58:61], vcc offset:64
	global_store_dwordx4 v156, v[50:53], vcc offset:512
	global_store_dwordx4 v156, v[42:45], vcc offset:576
	s_add_u32 vcc_lo, s18, 0x90000
	s_addc_u32 vcc_hi, s19, 0
	global_store_dwordx4 v156, v[54:57], vcc
	global_store_dwordx4 v156, v[46:49], vcc offset:64
	global_store_dwordx4 v156, v[34:37], vcc offset:512
	global_store_dwordx4 v156, v[26:29], vcc offset:576
	s_add_u32 vcc_lo, s18, 0xa0000
	s_addc_u32 vcc_hi, s19, 0
	global_store_dwordx4 v156, v[38:41], vcc
	global_store_dwordx4 v156, v[30:33], vcc offset:64
	global_store_dwordx4 v156, v[18:21], vcc offset:512
	global_store_dwordx4 v156, v[10:13], vcc offset:576
	s_add_u32 vcc_lo, s18, 0xb0000
	s_addc_u32 vcc_hi, s19, 0
	global_store_dwordx4 v156, v[22:25], vcc
	global_store_dwordx4 v156, v[14:17], vcc offset:64
	global_store_dwordx4 v156, v[6:9], vcc offset:512
	global_store_dwordx4 v156, v[2:5], vcc offset:576
	s_branch .Lres_pad0
	s_nop 0
	s_nop 0
	s_nop 0
	s_nop 0
	s_nop 0
	s_nop 0
	s_nop 0
	s_nop 0
	s_nop 0
	s_nop 0
	s_nop 0
	s_nop 0
	s_nop 0
	s_nop 0
	s_nop 0
	s_nop 0
	s_nop 0
	s_nop 0
	s_nop 0
	s_nop 0
	s_nop 0
	s_nop 0
	s_nop 0
	s_nop 0
	s_nop 0
	s_nop 0
	s_nop 0
	s_nop 0
	s_nop 0
	s_nop 0
	s_nop 0
	s_nop 0
	s_nop 0
	s_nop 0
	s_nop 0
	s_nop 0
	s_nop 0
	s_nop 0
	s_nop 0
	s_nop 0
	s_nop 0
	s_nop 0
	s_nop 0
	s_nop 0
	s_nop 0
	s_nop 0
	s_nop 0
	s_nop 0
	s_nop 0
	s_nop 0
	s_nop 0
	s_nop 0
	s_nop 0
	s_nop 0
	s_nop 0
	s_nop 0
	s_nop 0
	s_nop 0
	s_nop 0
.Lres_pad0:
	s_andn2_b64 vcc, exec, s[6:7]
	s_mov_b64 s[6:7], -1
	s_cbranch_vccnz .LBB0_145
	s_andn2_b64 vcc, exec, s[0:1]
	s_cbranch_vccnz .LBB0_144
	s_barrier
	s_branch .LBB0_144
